# L2 step loop unrolled by two, coefficient loads issued two steps ahead
# baseline (speedup 1.0000x reference)
.LBB0_281:
	s_waitcnt lgkmcnt(0)
	s_waitcnt vmcnt(0)
	v_mov_b64_e32 v[2:3], v[84:85]
	v_mov_b64_e32 v[4:5], v[86:87]
	v_mov_b64_e32 v[6:7], v[88:89]
	v_mov_b64_e32 v[8:9], v[90:91]
	v_mov_b64_e32 v[10:11], v[102:103]
	v_mov_b64_e32 v[12:13], v[104:105]
	v_mov_b64_e32 v[14:15], v[106:107]
	v_mov_b64_e32 v[16:17], v[108:109]
	v_mov_b64_e32 v[192:193], v[34:35]
	v_mov_b64_e32 v[194:195], v[32:33]
	v_mov_b64_e32 v[196:197], v[30:31]
	v_mov_b64_e32 v[198:199], v[28:29]
	v_mov_b64_e32 v[200:201], v[26:27]
	v_mov_b64_e32 v[202:203], v[24:25]
	v_mov_b64_e32 v[204:205], v[22:23]
	v_mov_b64_e32 v[206:207], v[20:21]
	s_mov_b32 s9, 1
	s_sub_i32 s8, 7, s9
	s_cmp_lt_u32 s9, 4
	s_cselect_b32 s8, s9, s8
	s_cmp_gt_u32 s9, 3
	s_cselect_b32 s74, 0x2200000, 0
	s_ashr_i32 s9, s8, 31
	s_lshl_b64 s[16:17], s[8:9], 15
	s_lshl_b64 s[8:9], s[8:9], 14
	v_lshl_add_u64 v[84:85], v[52:53], 0, s[74:75]
	v_lshl_add_u64 v[86:87], v[54:55], 0, s[8:9]
	v_lshl_add_u64 v[84:85], v[84:85], 0, s[16:17]
	global_load_dwordx4 v[208:211], v[84:85], off
	global_load_dwordx4 v[212:215], v[84:85], off offset:1024
	global_load_dwordx4 v[216:219], v[84:85], off offset:2048
	global_load_dwordx4 v[220:223], v[84:85], off offset:3072
	global_load_dwordx2 v[224:225], v[86:87], off
	global_load_dwordx2 v[226:227], v[86:87], off offset:512
	global_load_dwordx2 v[234:235], v[86:87], off offset:1024
	global_load_dwordx2 v[236:237], v[86:87], off offset:1536
.Ll2_stepA:
	s_add_i32 s12, s14, 1
	s_cmp_eq_u32 s14, 7
	s_cbranch_scc1 .Ll2_w0A
	s_waitcnt vmcnt(8)
	s_branch .Ll2_w1A

.Ll2_w1A:
	v_cvt_f32_f16_e32 v130, v2
	v_cvt_f32_f16_sdwa v146, v2 dst_sel:DWORD dst_unused:UNUSED_PAD src0_sel:WORD_1
	v_cvt_f32_f16_e32 v131, v3
	v_cvt_f32_f16_sdwa v147, v3 dst_sel:DWORD dst_unused:UNUSED_PAD src0_sel:WORD_1
	v_cvt_f32_f16_e32 v132, v4
	v_cvt_f32_f16_sdwa v148, v4 dst_sel:DWORD dst_unused:UNUSED_PAD src0_sel:WORD_1
	v_cvt_f32_f16_e32 v133, v5
	v_cvt_f32_f16_sdwa v149, v5 dst_sel:DWORD dst_unused:UNUSED_PAD src0_sel:WORD_1
	v_cvt_f32_f16_e32 v134, v6
	v_cvt_f32_f16_sdwa v150, v6 dst_sel:DWORD dst_unused:UNUSED_PAD src0_sel:WORD_1
	v_cvt_f32_f16_e32 v135, v7
	v_cvt_f32_f16_sdwa v151, v7 dst_sel:DWORD dst_unused:UNUSED_PAD src0_sel:WORD_1
	v_cvt_f32_f16_e32 v136, v8
	v_cvt_f32_f16_sdwa v152, v8 dst_sel:DWORD dst_unused:UNUSED_PAD src0_sel:WORD_1
	v_cvt_f32_f16_e32 v137, v9
	v_cvt_f32_f16_sdwa v153, v9 dst_sel:DWORD dst_unused:UNUSED_PAD src0_sel:WORD_1
	v_cvt_f32_f16_e32 v138, v10
	v_cvt_f32_f16_sdwa v154, v10 dst_sel:DWORD dst_unused:UNUSED_PAD src0_sel:WORD_1
	v_cvt_f32_f16_e32 v139, v11
	v_cvt_f32_f16_sdwa v155, v11 dst_sel:DWORD dst_unused:UNUSED_PAD src0_sel:WORD_1
	v_cvt_f32_f16_e32 v140, v12
	v_cvt_f32_f16_sdwa v156, v12 dst_sel:DWORD dst_unused:UNUSED_PAD src0_sel:WORD_1
	v_cvt_f32_f16_e32 v141, v13
	v_cvt_f32_f16_sdwa v157, v13 dst_sel:DWORD dst_unused:UNUSED_PAD src0_sel:WORD_1
	v_cvt_f32_f16_e32 v142, v14
	v_cvt_f32_f16_sdwa v158, v14 dst_sel:DWORD dst_unused:UNUSED_PAD src0_sel:WORD_1
	v_cvt_f32_f16_e32 v143, v15
	v_cvt_f32_f16_sdwa v159, v15 dst_sel:DWORD dst_unused:UNUSED_PAD src0_sel:WORD_1
	v_cvt_f32_f16_e32 v144, v16
	v_cvt_f32_f16_sdwa v160, v16 dst_sel:DWORD dst_unused:UNUSED_PAD src0_sel:WORD_1
	v_cvt_f32_f16_e32 v145, v17
	v_cvt_f32_f16_sdwa v161, v17 dst_sel:DWORD dst_unused:UNUSED_PAD src0_sel:WORD_1
	v_lshlrev_b32_e32 v162, 16, v56
	v_and_b32_e32 v163, 0xffff0000, v56
	v_lshlrev_b32_e32 v164, 16, v57
	v_and_b32_e32 v165, 0xffff0000, v57
	v_lshlrev_b32_e32 v166, 16, v58
	v_and_b32_e32 v167, 0xffff0000, v58
	v_lshlrev_b32_e32 v168, 16, v59
	v_and_b32_e32 v169, 0xffff0000, v59
	v_lshlrev_b32_e32 v170, 16, v60
	v_and_b32_e32 v171, 0xffff0000, v60
	v_lshlrev_b32_e32 v172, 16, v61
	v_and_b32_e32 v173, 0xffff0000, v61
	v_lshlrev_b32_e32 v174, 16, v62
	v_and_b32_e32 v175, 0xffff0000, v62
	v_lshlrev_b32_e32 v176, 16, v63
	v_and_b32_e32 v177, 0xffff0000, v63
	s_add_i32 s9, s14, 2
	s_cmp_gt_u32 s9, 7
	s_cbranch_scc1 .Ll2_noloadA
	s_sub_i32 s8, 7, s9
	s_cmp_lt_u32 s9, 4
	s_cselect_b32 s8, s9, s8
	s_cmp_gt_u32 s9, 3
	s_cselect_b32 s74, 0x2200000, 0
	s_ashr_i32 s9, s8, 31
	s_lshl_b64 s[16:17], s[8:9], 15
	s_lshl_b64 s[8:9], s[8:9], 14
	v_lshl_add_u64 v[84:85], v[52:53], 0, s[74:75]
	v_lshl_add_u64 v[86:87], v[54:55], 0, s[8:9]
	v_lshl_add_u64 v[84:85], v[84:85], 0, s[16:17]
	global_load_dwordx4 v[2:5], v[84:85], off
	global_load_dwordx4 v[6:9], v[84:85], off offset:1024
	global_load_dwordx4 v[10:13], v[84:85], off offset:2048
	global_load_dwordx4 v[14:17], v[84:85], off offset:3072
	global_load_dwordx2 v[56:57], v[86:87], off
	global_load_dwordx2 v[58:59], v[86:87], off offset:512
	global_load_dwordx2 v[60:61], v[86:87], off offset:1024
	global_load_dwordx2 v[62:63], v[86:87], off offset:1536
.Ll2_noloadA:
	s_cmp_lt_u32 s14, 4
	s_cselect_b32 s8, s14, s11
	s_lshl_b32 s13, s8, 12
	v_add_u32_e32 v81, s13, v125
	v_exp_f32_e32 v130, v130
	v_exp_f32_e32 v131, v131
	v_exp_f32_e32 v132, v132
	v_exp_f32_e32 v133, v133
	v_exp_f32_e32 v134, v134
	v_exp_f32_e32 v135, v135
	v_exp_f32_e32 v136, v136
	v_exp_f32_e32 v137, v137
	v_exp_f32_e32 v138, v138
	v_exp_f32_e32 v139, v139
	v_exp_f32_e32 v140, v140
	v_exp_f32_e32 v141, v141
	v_exp_f32_e32 v142, v142
	v_exp_f32_e32 v143, v143
	v_exp_f32_e32 v144, v144
	v_exp_f32_e32 v145, v145
	s_cmp_gt_u32 s14, 3
	s_cbranch_scc1 .Ll2_bwdA
	v_fmac_f32_dpp v146, v192, v130 row_shl:15 row_mask:0xf bank_mask:0xf bound_ctrl:1
	v_fmac_f32_dpp v147, v193, v131 row_shl:15 row_mask:0xf bank_mask:0xf bound_ctrl:1
	v_fmac_f32_dpp v148, v194, v132 row_shl:15 row_mask:0xf bank_mask:0xf bound_ctrl:1
	v_fmac_f32_dpp v149, v195, v133 row_shl:15 row_mask:0xf bank_mask:0xf bound_ctrl:1
	v_fmac_f32_dpp v150, v196, v134 row_shl:15 row_mask:0xf bank_mask:0xf bound_ctrl:1
	v_fmac_f32_dpp v151, v197, v135 row_shl:15 row_mask:0xf bank_mask:0xf bound_ctrl:1
	v_fmac_f32_dpp v152, v198, v136 row_shl:15 row_mask:0xf bank_mask:0xf bound_ctrl:1
	v_fmac_f32_dpp v153, v199, v137 row_shl:15 row_mask:0xf bank_mask:0xf bound_ctrl:1
	v_fmac_f32_dpp v154, v200, v138 row_shl:15 row_mask:0xf bank_mask:0xf bound_ctrl:1
	v_fmac_f32_dpp v155, v201, v139 row_shl:15 row_mask:0xf bank_mask:0xf bound_ctrl:1
	v_fmac_f32_dpp v156, v202, v140 row_shl:15 row_mask:0xf bank_mask:0xf bound_ctrl:1
	v_fmac_f32_dpp v157, v203, v141 row_shl:15 row_mask:0xf bank_mask:0xf bound_ctrl:1
	v_fmac_f32_dpp v158, v204, v142 row_shl:15 row_mask:0xf bank_mask:0xf bound_ctrl:1
	v_fmac_f32_dpp v159, v205, v143 row_shl:15 row_mask:0xf bank_mask:0xf bound_ctrl:1
	v_fmac_f32_dpp v160, v206, v144 row_shl:15 row_mask:0xf bank_mask:0xf bound_ctrl:1
	v_fmac_f32_dpp v161, v207, v145 row_shl:15 row_mask:0xf bank_mask:0xf bound_ctrl:1
	v_fmac_f32_dpp v146, v146, v130 row_shr:1 row_mask:0xf bank_mask:0xf bound_ctrl:1
	v_mul_f32_dpp v130, v130, v130 row_shr:1 row_mask:0xf bank_mask:0xf
	v_fmac_f32_dpp v147, v147, v131 row_shr:1 row_mask:0xf bank_mask:0xf bound_ctrl:1
	v_mul_f32_dpp v131, v131, v131 row_shr:1 row_mask:0xf bank_mask:0xf
	v_fmac_f32_dpp v148, v148, v132 row_shr:1 row_mask:0xf bank_mask:0xf bound_ctrl:1
	v_mul_f32_dpp v132, v132, v132 row_shr:1 row_mask:0xf bank_mask:0xf
	v_fmac_f32_dpp v149, v149, v133 row_shr:1 row_mask:0xf bank_mask:0xf bound_ctrl:1
	v_mul_f32_dpp v133, v133, v133 row_shr:1 row_mask:0xf bank_mask:0xf
	v_fmac_f32_dpp v150, v150, v134 row_shr:1 row_mask:0xf bank_mask:0xf bound_ctrl:1
	v_mul_f32_dpp v134, v134, v134 row_shr:1 row_mask:0xf bank_mask:0xf
	v_fmac_f32_dpp v151, v151, v135 row_shr:1 row_mask:0xf bank_mask:0xf bound_ctrl:1
	v_mul_f32_dpp v135, v135, v135 row_shr:1 row_mask:0xf bank_mask:0xf
	v_fmac_f32_dpp v152, v152, v136 row_shr:1 row_mask:0xf bank_mask:0xf bound_ctrl:1
	v_mul_f32_dpp v136, v136, v136 row_shr:1 row_mask:0xf bank_mask:0xf
	v_fmac_f32_dpp v153, v153, v137 row_shr:1 row_mask:0xf bank_mask:0xf bound_ctrl:1
	v_mul_f32_dpp v137, v137, v137 row_shr:1 row_mask:0xf bank_mask:0xf
	v_fmac_f32_dpp v154, v154, v138 row_shr:1 row_mask:0xf bank_mask:0xf bound_ctrl:1
	v_mul_f32_dpp v138, v138, v138 row_shr:1 row_mask:0xf bank_mask:0xf
	v_fmac_f32_dpp v155, v155, v139 row_shr:1 row_mask:0xf bank_mask:0xf bound_ctrl:1
	v_mul_f32_dpp v139, v139, v139 row_shr:1 row_mask:0xf bank_mask:0xf
	v_fmac_f32_dpp v156, v156, v140 row_shr:1 row_mask:0xf bank_mask:0xf bound_ctrl:1
	v_mul_f32_dpp v140, v140, v140 row_shr:1 row_mask:0xf bank_mask:0xf
	v_fmac_f32_dpp v157, v157, v141 row_shr:1 row_mask:0xf bank_mask:0xf bound_ctrl:1
	v_mul_f32_dpp v141, v141, v141 row_shr:1 row_mask:0xf bank_mask:0xf
	v_fmac_f32_dpp v158, v158, v142 row_shr:1 row_mask:0xf bank_mask:0xf bound_ctrl:1
	v_mul_f32_dpp v142, v142, v142 row_shr:1 row_mask:0xf bank_mask:0xf
	v_fmac_f32_dpp v159, v159, v143 row_shr:1 row_mask:0xf bank_mask:0xf bound_ctrl:1
	v_mul_f32_dpp v143, v143, v143 row_shr:1 row_mask:0xf bank_mask:0xf
	v_fmac_f32_dpp v160, v160, v144 row_shr:1 row_mask:0xf bank_mask:0xf bound_ctrl:1
	v_mul_f32_dpp v144, v144, v144 row_shr:1 row_mask:0xf bank_mask:0xf
	v_fmac_f32_dpp v161, v161, v145 row_shr:1 row_mask:0xf bank_mask:0xf bound_ctrl:1
	v_mul_f32_dpp v145, v145, v145 row_shr:1 row_mask:0xf bank_mask:0xf
	v_fmac_f32_dpp v146, v146, v130 row_shr:2 row_mask:0xf bank_mask:0xf bound_ctrl:1
	v_mul_f32_dpp v130, v130, v130 row_shr:2 row_mask:0xf bank_mask:0xf
	v_fmac_f32_dpp v147, v147, v131 row_shr:2 row_mask:0xf bank_mask:0xf bound_ctrl:1
	v_mul_f32_dpp v131, v131, v131 row_shr:2 row_mask:0xf bank_mask:0xf
	v_fmac_f32_dpp v148, v148, v132 row_shr:2 row_mask:0xf bank_mask:0xf bound_ctrl:1
	v_mul_f32_dpp v132, v132, v132 row_shr:2 row_mask:0xf bank_mask:0xf
	v_fmac_f32_dpp v149, v149, v133 row_shr:2 row_mask:0xf bank_mask:0xf bound_ctrl:1
	v_mul_f32_dpp v133, v133, v133 row_shr:2 row_mask:0xf bank_mask:0xf
	v_fmac_f32_dpp v150, v150, v134 row_shr:2 row_mask:0xf bank_mask:0xf bound_ctrl:1
	v_mul_f32_dpp v134, v134, v134 row_shr:2 row_mask:0xf bank_mask:0xf
	v_fmac_f32_dpp v151, v151, v135 row_shr:2 row_mask:0xf bank_mask:0xf bound_ctrl:1
	v_mul_f32_dpp v135, v135, v135 row_shr:2 row_mask:0xf bank_mask:0xf
	v_fmac_f32_dpp v152, v152, v136 row_shr:2 row_mask:0xf bank_mask:0xf bound_ctrl:1
	v_mul_f32_dpp v136, v136, v136 row_shr:2 row_mask:0xf bank_mask:0xf
	v_fmac_f32_dpp v153, v153, v137 row_shr:2 row_mask:0xf bank_mask:0xf bound_ctrl:1
	v_mul_f32_dpp v137, v137, v137 row_shr:2 row_mask:0xf bank_mask:0xf
	v_fmac_f32_dpp v154, v154, v138 row_shr:2 row_mask:0xf bank_mask:0xf bound_ctrl:1
	v_mul_f32_dpp v138, v138, v138 row_shr:2 row_mask:0xf bank_mask:0xf
	v_fmac_f32_dpp v155, v155, v139 row_shr:2 row_mask:0xf bank_mask:0xf bound_ctrl:1
	v_mul_f32_dpp v139, v139, v139 row_shr:2 row_mask:0xf bank_mask:0xf
	v_fmac_f32_dpp v156, v156, v140 row_shr:2 row_mask:0xf bank_mask:0xf bound_ctrl:1
	v_mul_f32_dpp v140, v140, v140 row_shr:2 row_mask:0xf bank_mask:0xf
	v_fmac_f32_dpp v157, v157, v141 row_shr:2 row_mask:0xf bank_mask:0xf bound_ctrl:1
	v_mul_f32_dpp v141, v141, v141 row_shr:2 row_mask:0xf bank_mask:0xf
	v_fmac_f32_dpp v158, v158, v142 row_shr:2 row_mask:0xf bank_mask:0xf bound_ctrl:1
	v_mul_f32_dpp v142, v142, v142 row_shr:2 row_mask:0xf bank_mask:0xf
	v_fmac_f32_dpp v159, v159, v143 row_shr:2 row_mask:0xf bank_mask:0xf bound_ctrl:1
	v_mul_f32_dpp v143, v143, v143 row_shr:2 row_mask:0xf bank_mask:0xf
	v_fmac_f32_dpp v160, v160, v144 row_shr:2 row_mask:0xf bank_mask:0xf bound_ctrl:1
	v_mul_f32_dpp v144, v144, v144 row_shr:2 row_mask:0xf bank_mask:0xf
	v_fmac_f32_dpp v161, v161, v145 row_shr:2 row_mask:0xf bank_mask:0xf bound_ctrl:1
	v_mul_f32_dpp v145, v145, v145 row_shr:2 row_mask:0xf bank_mask:0xf
	v_fmac_f32_dpp v146, v146, v130 row_shr:4 row_mask:0xf bank_mask:0xf bound_ctrl:1
	v_mul_f32_dpp v130, v130, v130 row_shr:4 row_mask:0xf bank_mask:0xf
	v_fmac_f32_dpp v147, v147, v131 row_shr:4 row_mask:0xf bank_mask:0xf bound_ctrl:1
	v_mul_f32_dpp v131, v131, v131 row_shr:4 row_mask:0xf bank_mask:0xf
	v_fmac_f32_dpp v148, v148, v132 row_shr:4 row_mask:0xf bank_mask:0xf bound_ctrl:1
	v_mul_f32_dpp v132, v132, v132 row_shr:4 row_mask:0xf bank_mask:0xf
	v_fmac_f32_dpp v149, v149, v133 row_shr:4 row_mask:0xf bank_mask:0xf bound_ctrl:1
	v_mul_f32_dpp v133, v133, v133 row_shr:4 row_mask:0xf bank_mask:0xf
	v_fmac_f32_dpp v150, v150, v134 row_shr:4 row_mask:0xf bank_mask:0xf bound_ctrl:1
	v_mul_f32_dpp v134, v134, v134 row_shr:4 row_mask:0xf bank_mask:0xf
	v_fmac_f32_dpp v151, v151, v135 row_shr:4 row_mask:0xf bank_mask:0xf bound_ctrl:1
	v_mul_f32_dpp v135, v135, v135 row_shr:4 row_mask:0xf bank_mask:0xf
	v_fmac_f32_dpp v152, v152, v136 row_shr:4 row_mask:0xf bank_mask:0xf bound_ctrl:1
	v_mul_f32_dpp v136, v136, v136 row_shr:4 row_mask:0xf bank_mask:0xf
	v_fmac_f32_dpp v153, v153, v137 row_shr:4 row_mask:0xf bank_mask:0xf bound_ctrl:1
	v_mul_f32_dpp v137, v137, v137 row_shr:4 row_mask:0xf bank_mask:0xf
	v_fmac_f32_dpp v154, v154, v138 row_shr:4 row_mask:0xf bank_mask:0xf bound_ctrl:1
	v_mul_f32_dpp v138, v138, v138 row_shr:4 row_mask:0xf bank_mask:0xf
	v_fmac_f32_dpp v155, v155, v139 row_shr:4 row_mask:0xf bank_mask:0xf bound_ctrl:1
	v_mul_f32_dpp v139, v139, v139 row_shr:4 row_mask:0xf bank_mask:0xf
	v_fmac_f32_dpp v156, v156, v140 row_shr:4 row_mask:0xf bank_mask:0xf bound_ctrl:1
	v_mul_f32_dpp v140, v140, v140 row_shr:4 row_mask:0xf bank_mask:0xf
	v_fmac_f32_dpp v157, v157, v141 row_shr:4 row_mask:0xf bank_mask:0xf bound_ctrl:1
	v_mul_f32_dpp v141, v141, v141 row_shr:4 row_mask:0xf bank_mask:0xf
	v_fmac_f32_dpp v158, v158, v142 row_shr:4 row_mask:0xf bank_mask:0xf bound_ctrl:1
	v_mul_f32_dpp v142, v142, v142 row_shr:4 row_mask:0xf bank_mask:0xf
	v_fmac_f32_dpp v159, v159, v143 row_shr:4 row_mask:0xf bank_mask:0xf bound_ctrl:1
	v_mul_f32_dpp v143, v143, v143 row_shr:4 row_mask:0xf bank_mask:0xf
	v_fmac_f32_dpp v160, v160, v144 row_shr:4 row_mask:0xf bank_mask:0xf bound_ctrl:1
	v_mul_f32_dpp v144, v144, v144 row_shr:4 row_mask:0xf bank_mask:0xf
	v_fmac_f32_dpp v161, v161, v145 row_shr:4 row_mask:0xf bank_mask:0xf bound_ctrl:1
	v_mul_f32_dpp v145, v145, v145 row_shr:4 row_mask:0xf bank_mask:0xf
	v_fmac_f32_dpp v146, v146, v130 row_shr:8 row_mask:0xf bank_mask:0xf bound_ctrl:1
	v_fmac_f32_dpp v147, v147, v131 row_shr:8 row_mask:0xf bank_mask:0xf bound_ctrl:1
	v_fmac_f32_dpp v148, v148, v132 row_shr:8 row_mask:0xf bank_mask:0xf bound_ctrl:1
	v_fmac_f32_dpp v149, v149, v133 row_shr:8 row_mask:0xf bank_mask:0xf bound_ctrl:1
	v_fmac_f32_dpp v150, v150, v134 row_shr:8 row_mask:0xf bank_mask:0xf bound_ctrl:1
	v_fmac_f32_dpp v151, v151, v135 row_shr:8 row_mask:0xf bank_mask:0xf bound_ctrl:1
	v_fmac_f32_dpp v152, v152, v136 row_shr:8 row_mask:0xf bank_mask:0xf bound_ctrl:1
	v_fmac_f32_dpp v153, v153, v137 row_shr:8 row_mask:0xf bank_mask:0xf bound_ctrl:1
	v_fmac_f32_dpp v154, v154, v138 row_shr:8 row_mask:0xf bank_mask:0xf bound_ctrl:1
	v_fmac_f32_dpp v155, v155, v139 row_shr:8 row_mask:0xf bank_mask:0xf bound_ctrl:1
	v_fmac_f32_dpp v156, v156, v140 row_shr:8 row_mask:0xf bank_mask:0xf bound_ctrl:1
	v_fmac_f32_dpp v157, v157, v141 row_shr:8 row_mask:0xf bank_mask:0xf bound_ctrl:1
	v_fmac_f32_dpp v158, v158, v142 row_shr:8 row_mask:0xf bank_mask:0xf bound_ctrl:1
	v_fmac_f32_dpp v159, v159, v143 row_shr:8 row_mask:0xf bank_mask:0xf bound_ctrl:1
	v_fmac_f32_dpp v160, v160, v144 row_shr:8 row_mask:0xf bank_mask:0xf bound_ctrl:1
	v_fmac_f32_dpp v161, v161, v145 row_shr:8 row_mask:0xf bank_mask:0xf bound_ctrl:1
	ds_write2st64_b32 v81, v146, v147 offset0:16 offset1:17
	ds_write2st64_b32 v81, v148, v149 offset0:18 offset1:19
	ds_write2st64_b32 v81, v150, v151 offset0:20 offset1:21
	ds_write2st64_b32 v81, v152, v153 offset0:22 offset1:23
	ds_write2st64_b32 v81, v154, v155 offset0:24 offset1:25
	ds_write2st64_b32 v81, v156, v157 offset0:26 offset1:27
	ds_write2st64_b32 v81, v158, v159 offset0:28 offset1:29
	ds_write2st64_b32 v81, v160, v161 offset0:30 offset1:31
	v_mov_b64_e32 v[192:193], v[146:147]
	v_mov_b64_e32 v[194:195], v[148:149]
	v_mov_b64_e32 v[196:197], v[150:151]
	v_mov_b64_e32 v[198:199], v[152:153]
	v_mov_b64_e32 v[200:201], v[154:155]
	v_mov_b64_e32 v[202:203], v[156:157]
	v_mov_b64_e32 v[204:205], v[158:159]
	v_mov_b64_e32 v[206:207], v[160:161]
	s_branch .Ll2_tailA

.Ll2_tailA:
	s_add_i32 s11, s11, -1
	v_subrev_u32_e32 v126, 64, v126
	s_mov_b32 s14, s12

.Ll2_w1B:
	v_cvt_f32_f16_e32 v130, v208
	v_cvt_f32_f16_sdwa v146, v208 dst_sel:DWORD dst_unused:UNUSED_PAD src0_sel:WORD_1
	v_cvt_f32_f16_e32 v131, v209
	v_cvt_f32_f16_sdwa v147, v209 dst_sel:DWORD dst_unused:UNUSED_PAD src0_sel:WORD_1
	v_cvt_f32_f16_e32 v132, v210
	v_cvt_f32_f16_sdwa v148, v210 dst_sel:DWORD dst_unused:UNUSED_PAD src0_sel:WORD_1
	v_cvt_f32_f16_e32 v133, v211
	v_cvt_f32_f16_sdwa v149, v211 dst_sel:DWORD dst_unused:UNUSED_PAD src0_sel:WORD_1
	v_cvt_f32_f16_e32 v134, v212
	v_cvt_f32_f16_sdwa v150, v212 dst_sel:DWORD dst_unused:UNUSED_PAD src0_sel:WORD_1
	v_cvt_f32_f16_e32 v135, v213
	v_cvt_f32_f16_sdwa v151, v213 dst_sel:DWORD dst_unused:UNUSED_PAD src0_sel:WORD_1
	v_cvt_f32_f16_e32 v136, v214
	v_cvt_f32_f16_sdwa v152, v214 dst_sel:DWORD dst_unused:UNUSED_PAD src0_sel:WORD_1
	v_cvt_f32_f16_e32 v137, v215
	v_cvt_f32_f16_sdwa v153, v215 dst_sel:DWORD dst_unused:UNUSED_PAD src0_sel:WORD_1
	v_cvt_f32_f16_e32 v138, v216
	v_cvt_f32_f16_sdwa v154, v216 dst_sel:DWORD dst_unused:UNUSED_PAD src0_sel:WORD_1
	v_cvt_f32_f16_e32 v139, v217
	v_cvt_f32_f16_sdwa v155, v217 dst_sel:DWORD dst_unused:UNUSED_PAD src0_sel:WORD_1
	v_cvt_f32_f16_e32 v140, v218
	v_cvt_f32_f16_sdwa v156, v218 dst_sel:DWORD dst_unused:UNUSED_PAD src0_sel:WORD_1
	v_cvt_f32_f16_e32 v141, v219
	v_cvt_f32_f16_sdwa v157, v219 dst_sel:DWORD dst_unused:UNUSED_PAD src0_sel:WORD_1
	v_cvt_f32_f16_e32 v142, v220
	v_cvt_f32_f16_sdwa v158, v220 dst_sel:DWORD dst_unused:UNUSED_PAD src0_sel:WORD_1
	v_cvt_f32_f16_e32 v143, v221
	v_cvt_f32_f16_sdwa v159, v221 dst_sel:DWORD dst_unused:UNUSED_PAD src0_sel:WORD_1
	v_cvt_f32_f16_e32 v144, v222
	v_cvt_f32_f16_sdwa v160, v222 dst_sel:DWORD dst_unused:UNUSED_PAD src0_sel:WORD_1
	v_cvt_f32_f16_e32 v145, v223
	v_cvt_f32_f16_sdwa v161, v223 dst_sel:DWORD dst_unused:UNUSED_PAD src0_sel:WORD_1
	v_lshlrev_b32_e32 v162, 16, v224
	v_and_b32_e32 v163, 0xffff0000, v224
	v_lshlrev_b32_e32 v164, 16, v225
	v_and_b32_e32 v165, 0xffff0000, v225
	v_lshlrev_b32_e32 v166, 16, v226
	v_and_b32_e32 v167, 0xffff0000, v226
	v_lshlrev_b32_e32 v168, 16, v227
	v_and_b32_e32 v169, 0xffff0000, v227
	v_lshlrev_b32_e32 v170, 16, v234
	v_and_b32_e32 v171, 0xffff0000, v234
	v_lshlrev_b32_e32 v172, 16, v235
	v_and_b32_e32 v173, 0xffff0000, v235
	v_lshlrev_b32_e32 v174, 16, v236
	v_and_b32_e32 v175, 0xffff0000, v236
	v_lshlrev_b32_e32 v176, 16, v237
	v_and_b32_e32 v177, 0xffff0000, v237
	s_add_i32 s9, s14, 2
	s_cmp_gt_u32 s9, 7
	s_cbranch_scc1 .Ll2_noloadB
	s_sub_i32 s8, 7, s9
	s_cmp_lt_u32 s9, 4
	s_cselect_b32 s8, s9, s8
	s_cmp_gt_u32 s9, 3
	s_cselect_b32 s74, 0x2200000, 0
	s_ashr_i32 s9, s8, 31
	s_lshl_b64 s[16:17], s[8:9], 15
	s_lshl_b64 s[8:9], s[8:9], 14
	v_lshl_add_u64 v[84:85], v[52:53], 0, s[74:75]
	v_lshl_add_u64 v[86:87], v[54:55], 0, s[8:9]
	v_lshl_add_u64 v[84:85], v[84:85], 0, s[16:17]
	global_load_dwordx4 v[208:211], v[84:85], off
	global_load_dwordx4 v[212:215], v[84:85], off offset:1024
	global_load_dwordx4 v[216:219], v[84:85], off offset:2048
	global_load_dwordx4 v[220:223], v[84:85], off offset:3072
	global_load_dwordx2 v[224:225], v[86:87], off
	global_load_dwordx2 v[226:227], v[86:87], off offset:512
	global_load_dwordx2 v[234:235], v[86:87], off offset:1024
	global_load_dwordx2 v[236:237], v[86:87], off offset:1536

.Ll2_tailB:
	s_add_i32 s11, s11, -1
	v_subrev_u32_e32 v126, 64, v126
	s_mov_b32 s14, s12
	s_cmp_eq_u32 s14, 8
	s_cbranch_scc0 .Ll2_stepA
	s_waitcnt vmcnt(0)
	s_add_i32 s26, s10, s43
	s_ashr_i32 s27, s26, 31
	s_lshl_b64 s[28:29], s[26:27], 10
	v_readlane_b32 s76, v255, 54
	v_readlane_b32 s77, v255, 55
	v_lshrrev_b32_e32 v162, 4, v228
	v_and_b32_e32 v163, 15, v228
	v_lshlrev_b32_e32 v163, 4, v163
	s_add_u32 s76, s76, s28
	s_addc_u32 s77, s77, s29
	v_lshl_add_u32 v162, v162, 10, v163
	v_add_u32_e32 v163, 0x1000, v162
	global_load_dwordx4 v[130:133], v162, s[76:77]
	global_load_dwordx4 v[134:137], v162, s[76:77] offset:256
	global_load_dwordx4 v[138:141], v162, s[76:77] offset:512
	global_load_dwordx4 v[142:145], v162, s[76:77] offset:768
	global_load_dwordx4 v[146:149], v163, s[76:77]
	global_load_dwordx4 v[150:153], v163, s[76:77] offset:256
	global_load_dwordx4 v[154:157], v163, s[76:77] offset:512
	global_load_dwordx4 v[158:161], v163, s[76:77] offset:768
